# speedup vs baseline: 1.0103x; 1.0103x over previous
;   __device__ __forceinline__ bf16_t* Z() const { return (bf16_t*)(ws + 456 * MB); }
; __device__ __forceinline__ float opaque_zero() { float z; asm volatile("v_mov_b32 %0, 0" : "=v"(z)); return z; }
; #define opaque_tid() opaque_tid_w(p.wave)
; #define LAS __attribute__((address_space(3)))
; __device__ __forceinline__ int v_rd_base(int lane) { return ((lane & 3) << 3) | (((lane >> 2) & 3) << 6) | (((lane >> 4) & 1) << 5) | (((lane >> 5) & 1) << 8); }
; __device__ __forceinline__ void attn_fused(const Params& p, int layer, float lam, float lam_init, int q0, int tok0, int h, int seq, char* lds) {
;   const int tid = opaque_tid(), wid = __builtin_amdgcn_readfirstlane(tid >> 6), lane = tid & 63, r32 = lane & 31, hi = lane >> 5;
;   LAS unsigned char* ldsl = (LAS unsigned char*)lds;
;   float* ws = (float*)(lds + AF_WS) + wid * 128; float* al_l = ws; float* li0 = ws + 32; float* li1 = ws + 64;
;   const bf16_t* Kh = p.Z() + (size_t)tok0 * LDZ + 1024 + h * 128; const bf16_t* Vh = p.Z() + (size_t)tok0 * LDZ + 2048 + h * 128;
;   unsigned kofs[2], vofs[2];
; #pragma unroll
;   for (int i = 0; i < 2; ++i) { const int L = (i * 8 + wid) * 64 + lane, row = L >> 4, ch = (L & 15) ^ (row & 15); kofs[i] = (unsigned)(row * LDZ + ch * 8);
;     const int sub = L >> 5, kk = (sub >> 2) * 8 + ((L & 31) >> 2), c = (sub & 3) * 32 + (L & 3) * 8, k = (kk & ~0xC) | ((kk & 4) << 1) | ((kk & 8) >> 1); vofs[i] = (unsigned)(k * LDZ + c); }
;     ...
;   ADMA(0, 0);
;   f32x16 oa[4], ob[4];
;   { const float z0 = opaque_zero();
; #pragma unroll
;     for (int d = 0; d < 4; ++d)
; #pragma unroll
;       for (int r = 0; r < 16; ++r) { oa[d][r] = z0; ob[d][r] = z0; } }
;   bf16x8 qr[8];
;   { const bf16_t* Qw = p.Z() + (size_t)(q0 + wid * 32 + r32) * LDZ + h * 128 + hi * 8;
; #pragma unroll
;     for (int d0 = 0; d0 < 8; ++d0) qr[d0] = *(const bf16x8*)(Qw + d0 * 16); }
;   float m0 = -1e30f, m1 = -1e30f, l0 = 0.f, l1 = 0.f;
;   const int vb0 = (int)(uintptr_t)(lds + AF_V) + v_rd_base(lane);
;   asm volatile("s_waitcnt vmcnt(0)" ::: "memory"); __syncthreads();
.LBB0_120:
	v_mbcnt_lo_u32_b32 v24, -1, 0
	v_mbcnt_hi_u32_b32 v24, -1, v24
	s_lshl_b32 s2, s2, 8
	v_add_u32_e32 v0, s40, v24
	s_add_i32 s2, s1, s2
	v_readfirstlane_b32 s6, v0
	s_ashr_i32 s12, s6, 6
	s_lshl_b32 s34, s12, 9
	s_add_i32 s34, s34, 0x10000
	s_mul_i32 s14, s1, 0x2800
	s_mul_hi_i32 s13, s1, 0x2800
	s_add_u32 s1, s46, s14
	v_bfe_u32 v1, v0, 2, 3
	v_lshrrev_b32_e32 v0, 1, v0
	s_addc_u32 s7, s47, s13
	s_and_b32 s15, s6, 0xffffffc0
	v_mov_b32_e32 v0, s6
	s_movk_i32 s6, 0xffc0
	v_bfi_b32 v0, s6, v0, v24
	s_ashr_i32 s6, s15, 4
	v_ashrrev_i32_e32 v0, 4, v0
	s_and_b32 s16, s6, 0x3ffff0
	v_xor_b32_e32 v2, v0, v24
	s_and_b32 s6, s6, 8
	v_mul_lo_u32 v0, v0, s89
	v_lshlrev_b32_e32 v2, 3, v2
	s_or_b32 s6, s16, s6
	v_and_b32_e32 v25, 63, v24
	v_lshlrev_b32_e32 v26, 3, v24
	v_and_or_b32 v192, v2, s66, v0
	v_mov_b32_e32 v5, 0x60
	v_or_b32_e32 v2, s6, v1
	v_and_b32_e32 v3, 24, v26
	v_bitop3_b32 v0, s15, v5, v25 bitop3:0xc8
	v_mul_u32_u24_e32 v2, 0x1400, v2
	s_addk_i32 s15, 0x200
	v_or3_b32 v0, v2, v0, v3
	v_or_b32_e32 v2, s15, v25
	v_ashrrev_i32_e32 v2, 4, v2
	v_xor_b32_e32 v4, v2, v24
	v_mul_lo_u32 v2, v2, s89
	v_lshlrev_b32_e32 v4, 3, v4
	s_ashr_i32 s6, s15, 4
	v_and_or_b32 v2, v4, s66, v2
	v_bitop3_b32 v4, s15, v5, v25 bitop3:0xc8
	s_and_b32 s15, s6, 0x3ffff0
	s_and_b32 s6, s6, 8
	s_lshl_b32 s8, s48, 7
	s_or_b32 s6, s15, s6
	s_lshl_b32 s60, s48, 8
	v_or_b32_e32 v1, s6, v1
	s_add_u32 s6, s1, s60
	s_addc_u32 s7, s7, 0
	v_mul_u32_u24_e32 v1, 0x1400, v1
	s_add_u32 s50, s6, 0x1000
	v_lshlrev_b64 v[16:17], 1, v[192:193]
	v_or3_b32 v4, v1, v4, v3
	s_addc_u32 s51, s7, 0
	s_lshl_b32 s35, s12, 10
	v_lshl_add_u64 v[6:7], s[6:7], 0, v[16:17]
	s_mov_b64 s[16:17], 0x800
	v_mov_b32_e32 v1, v193
	v_lshl_add_u64 v[6:7], v[6:7], 0, s[16:17]
	s_mov_b32 m0, s35
	v_lshlrev_b64 v[18:19], 1, v[0:1]
	v_mov_b32_e32 v3, v193
	global_load_lds_dwordx4 v[6:7], off
	v_lshl_add_u64 v[0:1], s[50:51], 0, v[18:19]
	s_add_i32 m0, s35, 0x8000
	v_lshlrev_b64 v[20:21], 1, v[2:3]
	global_load_lds_dwordx4 v[0:1], off
	v_lshl_add_u64 v[0:1], s[6:7], 0, v[20:21]
	v_mov_b32_e32 v5, v193
	v_lshl_add_u64 v[0:1], v[0:1], 0, s[16:17]
	s_add_i32 m0, s35, 0x2000
	v_lshlrev_b64 v[22:23], 1, v[4:5]
	s_lshl_b32 s1, s12, 5
	v_and_b32_e32 v204, 31, v24
	global_load_lds_dwordx4 v[0:1], off
	v_lshl_add_u64 v[0:1], s[50:51], 0, v[22:23]
	s_add_i32 m0, s35, 0xa000
	s_add_i32 s1, s2, s1
	global_load_lds_dwordx4 v[0:1], off
	v_add_u32_e32 v1, s1, v204
	v_mov_b64_e32 v[2:3], s[46:47]
	v_bfe_u32 v205, v24, 5, 1
	v_mad_i64_i32 v[2:3], s[6:7], v1, s41, v[2:3]
	v_lshl_add_u64 v[2:3], v[2:3], 0, s[60:61]
	v_lshlrev_b32_e32 v192, 4, v205
	v_lshl_add_u64 v[2:3], v[2:3], 0, v[192:193]
	v_mov_b32 v0, 0
	global_load_dwordx4 v[160:163], v[2:3], off
	global_load_dwordx4 v[164:167], v[2:3], off offset:32
	global_load_dwordx4 v[168:171], v[2:3], off offset:64
	global_load_dwordx4 v[172:175], v[2:3], off offset:96
	global_load_dwordx4 v[176:179], v[2:3], off offset:128
	global_load_dwordx4 v[180:183], v[2:3], off offset:160
	global_load_dwordx4 v[184:187], v[2:3], off offset:192
	global_load_dwordx4 v[188:191], v[2:3], off offset:224
	v_lshlrev_b32_e32 v27, 1, v24
	v_lshlrev_b32_e32 v24, 4, v24
	s_movk_i32 s2, 0xf0
	v_and_b32_e32 v28, 0xf0, v24
	v_bitop3_b32 v227, v192, v24, s2 bitop3:0x78
	s_movk_i32 s2, 0x80
	v_bitop3_b32 v231, v192, v28, s2 bitop3:0x36
	s_movk_i32 s2, 0xa0
	s_mov_b32 s49, s61
	v_bitop3_b32 v232, v192, v28, s2 bitop3:0x36
	s_movk_i32 s2, 0xe0
	s_lshl_b64 s[48:49], s[48:49], 8
	v_bitop3_b32 v234, v192, v28, s2 bitop3:0x36
	s_add_u32 s2, s14, s48
	s_addc_u32 s12, s13, s49
	s_add_u32 s48, s68, s2
	s_addc_u32 s49, s69, s12
	v_and_b32_e32 v27, 32, v27
	v_lshl_add_u64 v[194:195], s[48:49], 0, v[20:21]
	v_lshl_add_u64 v[196:197], s[48:49], 0, v[16:17]
	s_add_u32 s48, s70, s2
	s_waitcnt vmcnt(0)
	v_mov_b32_e32 v14, v0
	v_mov_b32_e32 v15, v0
	v_and_b32_e32 v26, 0x118, v26
	v_and_or_b32 v24, v24, s86, v27
	s_addc_u32 s49, s71, s12
	v_mov_b32_e32 v1, v0
	v_mov_b32_e32 v2, v0
	v_mov_b32_e32 v3, v0
	v_mov_b32_e32 v4, v0
	v_mov_b32_e32 v5, v0
	v_mov_b32_e32 v6, v0
	v_mov_b32_e32 v7, v0
	v_mov_b32_e32 v8, v0
	v_mov_b32_e32 v9, v0
	v_mov_b32_e32 v10, v0
	v_mov_b32_e32 v11, v0
	v_mov_b32_e32 v12, v0
	v_mov_b32_e32 v13, v0
	v_bitop3_b32 v228, v192, v28, 32 bitop3:0x36
	v_bitop3_b32 v229, v192, v28, 64 bitop3:0x36
	v_bitop3_b32 v230, v192, v28, s87 bitop3:0x36
	v_cmp_gt_u32_e64 s[6:7], 32, v25
	v_bitop3_b32 v233, v192, v28, s86 bitop3:0x36
	v_or3_b32 v235, v24, v26, s88
	v_lshl_add_u64 v[198:199], s[48:49], 0, v[18:19]
	v_lshl_add_u64 v[200:201], s[48:49], 0, v[22:23]
	v_mov_b64_e32 v[78:79], v[14:15]
	v_mov_b64_e32 v[46:47], v[14:15]
	v_mov_b64_e32 v[30:31], v[14:15]
	v_mov_b64_e32 v[126:127], v[14:15]
	v_mov_b64_e32 v[110:111], v[14:15]
	v_mov_b64_e32 v[94:95], v[14:15]
	v_mov_b64_e32 v[62:63], v[14:15]
	s_mov_b32 s60, 1
	v_lshlrev_b32_e32 v206, 8, v204
	v_lshl_or_b32 v207, v204, 2, s34
	v_mov_b32_e32 v241, 0xf149f2ca
	v_mov_b32_e32 v237, 0
	s_mov_b64 s[48:49], 0
	v_mov_b64_e32 v[76:77], v[12:13]
	v_mov_b64_e32 v[74:75], v[10:11]
	v_mov_b64_e32 v[72:73], v[8:9]
	v_mov_b64_e32 v[70:71], v[6:7]
	v_mov_b64_e32 v[68:69], v[4:5]
	v_mov_b64_e32 v[66:67], v[2:3]
	v_mov_b64_e32 v[64:65], v[0:1]
	v_mov_b64_e32 v[44:45], v[12:13]
	v_mov_b64_e32 v[42:43], v[10:11]
	v_mov_b64_e32 v[40:41], v[8:9]
	v_mov_b64_e32 v[38:39], v[6:7]
	v_mov_b64_e32 v[36:37], v[4:5]
	v_mov_b64_e32 v[34:35], v[2:3]
	v_mov_b64_e32 v[32:33], v[0:1]
	v_mov_b64_e32 v[28:29], v[12:13]
	v_mov_b64_e32 v[26:27], v[10:11]
	v_mov_b64_e32 v[24:25], v[8:9]
	v_mov_b64_e32 v[22:23], v[6:7]
	v_mov_b64_e32 v[20:21], v[4:5]
	v_mov_b64_e32 v[18:19], v[2:3]
	v_mov_b64_e32 v[16:17], v[0:1]
	v_mov_b64_e32 v[124:125], v[12:13]
	v_mov_b64_e32 v[122:123], v[10:11]
	v_mov_b64_e32 v[120:121], v[8:9]
	v_mov_b64_e32 v[118:119], v[6:7]
	v_mov_b64_e32 v[116:117], v[4:5]
	v_mov_b64_e32 v[114:115], v[2:3]
	v_mov_b64_e32 v[112:113], v[0:1]
	v_mov_b64_e32 v[108:109], v[12:13]
	v_mov_b64_e32 v[106:107], v[10:11]
	v_mov_b64_e32 v[104:105], v[8:9]
	v_mov_b64_e32 v[102:103], v[6:7]
	v_mov_b64_e32 v[100:101], v[4:5]
	v_mov_b64_e32 v[98:99], v[2:3]
	v_mov_b64_e32 v[96:97], v[0:1]
	v_mov_b64_e32 v[92:93], v[12:13]
	v_mov_b64_e32 v[90:91], v[10:11]
	v_mov_b64_e32 v[88:89], v[8:9]
	v_mov_b64_e32 v[86:87], v[6:7]
	v_mov_b64_e32 v[84:85], v[4:5]
	v_mov_b64_e32 v[82:83], v[2:3]
	v_mov_b64_e32 v[80:81], v[0:1]
	v_mov_b64_e32 v[60:61], v[12:13]
	v_mov_b64_e32 v[58:59], v[10:11]
	v_mov_b64_e32 v[56:57], v[8:9]
	v_mov_b64_e32 v[54:55], v[6:7]
	v_mov_b64_e32 v[52:53], v[4:5]
	v_mov_b64_e32 v[50:51], v[2:3]
	v_mov_b64_e32 v[48:49], v[0:1]
	v_mov_b32_e32 v238, 0
	v_mov_b32_e32 v243, 0xf149f2ca
	s_waitcnt vmcnt(0) lgkmcnt(0)
	s_barrier

; __device__ __forceinline__ void partialSM(f32x16& p0, f32x16& p1, float& m_reg, float& mn, float& alpha) {
;   float pmax = p0[0];
; #pragma unroll
;   for (int r = 1; r < 16; ++r) pmax = fmaxf(pmax, p0[r]);
; #pragma unroll
;   for (int r = 0; r < 16; ++r) pmax = fmaxf(pmax, p1[r]);
;   { auto rr = __builtin_amdgcn_permlane32_swap(__float_as_uint(pmax), __float_as_uint(pmax), false, false);
;     pmax = fmaxf(__uint_as_float(rr[0]), __uint_as_float(rr[1])); }
;   if (__builtin_expect(__all(pmax - m_reg <= AT_THR * 1.4426950408889634f), 1)) { mn = m_reg; alpha = 1.f; }
;   else { mn = fmaxf(m_reg, pmax); alpha = __builtin_amdgcn_exp2f(m_reg - mn); m_reg = mn; }
; __device__ __forceinline__ void qkt2(f32x16& p0, f32x16& p1, const char* Ks, const bf16x8* qr, int r32, int hi, int cbase) {
; #pragma unroll
;   for (int r = 0; r < 16; ++r) { p0[r] = 0.f; p1[r] = 0.f; }
; #pragma unroll
;   for (int d0 = 0; d0 < 4; ++d0) { const int cb = cbase + (d0 * 16 + hi * 8) * 2;
;     const bf16x8 b0 = *reinterpret_cast<const bf16x8*>(Ks + KSWZ(r32, cb));
;     const bf16x8 b1 = *reinterpret_cast<const bf16x8*>(Ks + KSWZ(32 + r32, cb));
;     p0 = __builtin_amdgcn_mfma_f32_32x32x16_bf16(b0, qr[d0], p0, 0, 0, 0);
;     p1 = __builtin_amdgcn_mfma_f32_32x32x16_bf16(b1, qr[d0], p1, 0, 0, 0); }
; }
.LBB0_125:
	v_add3_u32 v128, s2, v227, v206
	ds_read_b128 v[128:131], v128
	v_add_u32_e32 v242, s2, v206
	v_add_u32_e32 v132, v242, v227
	v_add3_u32 v208, s2, v228, v206
	ds_read_b128 v[132:135], v132 offset:8192
	ds_read_b128 v[244:247], v208
	v_add_u32_e32 v208, v242, v228
	ds_read_b128 v[248:251], v208 offset:8192
	v_add3_u32 v208, s2, v229, v206
	s_waitcnt lgkmcnt(0)
	v_mfma_f32_32x32x16_bf16 v[144:159], v[128:131], v[160:163], 0
	v_mfma_f32_32x32x16_bf16 v[128:143], v[132:135], v[160:163], 0
	v_mfma_f32_32x32x16_bf16 v[144:159], v[244:247], v[164:167], v[144:159]
	ds_read_b128 v[244:247], v208
	v_add_u32_e32 v208, v242, v229
	v_mfma_f32_32x32x16_bf16 v[128:143], v[248:251], v[164:167], v[128:143]
	ds_read_b128 v[248:251], v208 offset:8192
	v_add3_u32 v208, s2, v230, v206
	s_waitcnt lgkmcnt(0)
	v_mfma_f32_32x32x16_bf16 v[144:159], v[244:247], v[168:171], v[144:159]
	ds_read_b128 v[244:247], v208
	v_add_u32_e32 v208, v242, v230
	v_mfma_f32_32x32x16_bf16 v[128:143], v[248:251], v[168:171], v[128:143]
	ds_read_b128 v[248:251], v208 offset:8192
	s_waitcnt lgkmcnt(0)
	v_mfma_f32_32x32x16_bf16 v[144:159], v[244:247], v[172:175], v[144:159]
	v_mfma_f32_32x32x16_bf16 v[128:143], v[248:251], v[172:175], v[128:143]
	s_nop 10
	v_max3_f32 v208, v144, v145, v146
	v_max3_f32 v209, v152, v153, v154
	v_max3_f32 v208, v208, v147, v148
	v_max3_f32 v209, v209, v155, v156
	v_max3_f32 v208, v208, v149, v150
	v_max3_f32 v209, v209, v157, v158
	v_max3_f32 v208, v208, v151, v159
	v_max3_f32 v210, v128, v129, v130
	v_max3_f32 v211, v136, v137, v138
	v_max3_f32 v210, v210, v131, v132
	v_max3_f32 v211, v211, v139, v140
	v_max3_f32 v210, v210, v133, v134
	v_max3_f32 v211, v211, v141, v142
	v_max3_f32 v210, v210, v135, v143
	v_max3_f32 v208, v208, v209, v210
	v_max_f32_e32 v208, v208, v211
	v_mov_b32_e32 v209, v208
	s_nop 1
	v_permlane32_swap_b32_e32 v208, v209
	v_max_f32_e32 v236, v208, v209
	v_sub_f32_e32 v208, v236, v243
	v_cmp_ge_f32_e32 vcc, s0, v208
	s_cmp_lg_u64 vcc, exec
	s_cbranch_scc1 .LBB0_141
	v_mov_b32_e32 v239, v243
	v_mov_b32_e32 v240, 1.0
	v_mov_b32_e32 v236, v243
	s_branch .LBB0_132

; __device__ __forceinline__ void partialSM(f32x16& p0, f32x16& p1, float& m_reg, float& mn, float& alpha) {
;     ...
;   p0 = p0 - mn; p1 = p1 - mn;
; #pragma unroll
;   for (int r = 0; r < 16; ++r) p0[r] = __builtin_amdgcn_exp2f(p0[r]);
; }
; __device__ __forceinline__ void finishSM(f32x16& p0, f32x16& p1, float alpha, float& l_reg, bf16x8& pa0, bf16x8& pa1, bf16x8& pa2, bf16x8& pa3) {
; #pragma unroll
;   for (int r = 0; r < 16; ++r) p1[r] = __builtin_amdgcn_exp2f(p1[r]);
;   float ps = 0;
; #pragma unroll
;   for (int r = 0; r < 16; ++r) ps += p0[r];
; #pragma unroll
;   for (int r = 0; r < 16; ++r) ps += p1[r];
;   { auto rr = __builtin_amdgcn_permlane32_swap(__float_as_uint(ps), __float_as_uint(ps), false, false);
;     ps = __uint_as_float(rr[0]) + __uint_as_float(rr[1]); }
;   l_reg = l_reg * alpha + ps;
;     ...
;   PK4(p0, 0, pa0); PK4(p0, 8, pa1); PK4(p1, 0, pa2); PK4(p1, 8, pa3);
;     ...
; }
; __device__ __forceinline__ void qkt(f32x16& p0, f32x16& p1, const char* Ks, const bf16x8* qr, int r32, int hi) {
; #pragma unroll
;   for (int r = 0; r < 16; ++r) { p0[r] = 0.f; p1[r] = 0.f; }
; #pragma unroll
;   for (int d0 = 0; d0 < 4; ++d0) { const int ch = d0 * 2 + hi;
;     const bf16x8 b0 = *reinterpret_cast<const bf16x8*>(Ks + KSW(r32, ch));
;     const bf16x8 b1 = *reinterpret_cast<const bf16x8*>(Ks + KSW(32 + r32, ch));
;     p0 = __builtin_amdgcn_mfma_f32_32x32x16_bf16(b0, qr[d0], p0, 0, 0, 0);
;     p1 = __builtin_amdgcn_mfma_f32_32x32x16_bf16(b1, qr[d0], p1, 0, 0, 0); }
; }
; __device__ __forceinline__ int v_st(int k, int c) { const int kk = (k & ~0xC) | ((k & 4) << 1) | ((k & 8) >> 1); return ((kk >> 3) * 4 + (c >> 5)) * 512 + ((kk & 7) * 32 + (c & 31)) * 2; }
; __device__ __forceinline__ int v_rd_base(int lane) { return ((lane & 3) << 3) | (((lane >> 2) & 3) << 6) | (((lane >> 4) & 1) << 5) | (((lane >> 5) & 1) << 8); }
; template <int OFF> __device__ __forceinline__ s16x4 tr_read(int vb) {
;   s16x4 r; asm volatile("ds_read_b64_tr_b16 %0, %1 offset:%2" : "=&v"(r) : "v"(vb), "i"(OFF) : "memory"); return r;
; }
; template <int D0> __device__ __forceinline__ void pv_one(f32x16& od, int vb, bf16x8 pa0, bf16x8 pa1, bf16x8 pa2, bf16x8 pa3) {
;   const s16x4 l0 = tr_read<v_rd_off(D0, 0, 0)>(vb), h0 = tr_read<v_rd_off(D0, 0, 1)>(vb), l1 = tr_read<v_rd_off(D0, 1, 0)>(vb), h1 = tr_read<v_rd_off(D0, 1, 1)>(vb);
.LBB0_132:
	v_sub_f32_e32 v144, v144, v239
	v_sub_f32_e32 v145, v145, v239
	v_exp_f32_e32 v144, v144
	v_sub_f32_e32 v146, v146, v239
	v_exp_f32_e32 v145, v145
	v_sub_f32_e32 v147, v147, v239
	v_exp_f32_e32 v146, v146
	v_sub_f32_e32 v148, v148, v239
	v_sub_f32_e32 v128, v128, v239
	v_exp_f32_e32 v147, v147
	v_sub_f32_e32 v149, v149, v239
	v_exp_f32_e32 v148, v148
	v_exp_f32_e32 v208, v128
	v_sub_f32_e32 v150, v150, v239
	v_exp_f32_e32 v149, v149
	v_add_f32_e32 v128, v145, v144
	v_sub_f32_e32 v151, v151, v239
	v_exp_f32_e32 v150, v150
	v_add_f32_e32 v128, v146, v128
	v_sub_f32_e32 v152, v152, v239
	v_exp_f32_e32 v151, v151
	v_add_f32_e32 v128, v147, v128
	v_sub_f32_e32 v153, v153, v239
	v_exp_f32_e32 v152, v152
	v_add_f32_e32 v128, v148, v128
	v_sub_f32_e32 v154, v154, v239
	v_exp_f32_e32 v153, v153
	v_add_f32_e32 v128, v149, v128
	v_sub_f32_e32 v155, v155, v239
	v_exp_f32_e32 v154, v154
	v_add_f32_e32 v128, v150, v128
	v_sub_f32_e32 v156, v156, v239
	v_exp_f32_e32 v155, v155
	v_add_f32_e32 v128, v151, v128
	v_sub_f32_e32 v157, v157, v239
	v_exp_f32_e32 v156, v156
	v_add_f32_e32 v128, v152, v128
	v_sub_f32_e32 v158, v158, v239
	v_exp_f32_e32 v157, v157
	v_add_f32_e32 v128, v153, v128
	v_sub_f32_e32 v159, v159, v239
	v_exp_f32_e32 v158, v158
	v_add_f32_e32 v128, v154, v128
	v_exp_f32_e32 v159, v159
	v_add_f32_e32 v128, v155, v128
	v_sub_f32_e32 v129, v129, v239
	v_add_f32_e32 v128, v156, v128
	v_sub_f32_e32 v130, v130, v239
	v_exp_f32_e32 v209, v129
	v_add_f32_e32 v128, v157, v128
	v_sub_f32_e32 v131, v131, v239
	v_exp_f32_e32 v210, v130
	v_add_f32_e32 v128, v158, v128
	v_sub_f32_e32 v132, v132, v239
	v_exp_f32_e32 v211, v131
	v_add_f32_e32 v128, v159, v128
	v_sub_f32_e32 v133, v133, v239
	v_exp_f32_e32 v216, v132
	v_add_f32_e32 v128, v208, v128
	v_sub_f32_e32 v134, v134, v239
	v_exp_f32_e32 v217, v133
	v_add_f32_e32 v128, v209, v128
	v_sub_f32_e32 v135, v135, v239
	v_exp_f32_e32 v218, v134
	v_add_f32_e32 v128, v210, v128
	v_sub_f32_e32 v136, v136, v239
	v_exp_f32_e32 v219, v135
	v_add_f32_e32 v128, v211, v128
	v_sub_f32_e32 v137, v137, v239
	v_exp_f32_e32 v222, v136
	v_add_f32_e32 v128, v216, v128
	v_sub_f32_e32 v138, v138, v239
	v_exp_f32_e32 v223, v137
	v_add_f32_e32 v128, v217, v128
	v_sub_f32_e32 v139, v139, v239
	v_exp_f32_e32 v224, v138
	v_add_f32_e32 v128, v218, v128
	v_sub_f32_e32 v140, v140, v239
	v_exp_f32_e32 v225, v139
	v_add_f32_e32 v128, v219, v128
	v_sub_f32_e32 v141, v141, v239
	v_exp_f32_e32 v245, v140
	v_add_f32_e32 v128, v222, v128
	v_sub_f32_e32 v142, v142, v239
	v_exp_f32_e32 v246, v141
	v_add_f32_e32 v128, v223, v128
	v_sub_f32_e32 v143, v143, v239
	v_exp_f32_e32 v247, v142
	v_add_f32_e32 v128, v224, v128
	v_exp_f32_e32 v143, v143
	v_add_f32_e32 v128, v225, v128
	v_add_f32_e32 v128, v245, v128
	v_add_f32_e32 v128, v246, v128
	v_add_f32_e32 v128, v247, v128
	v_add_f32_e32 v243, v143, v128
	v_mov_b32_e32 v244, v243
	v_cvt_pk_bf16_f32 v128, v144, v145
	v_cvt_pk_bf16_f32 v129, v146, v147
	v_cvt_pk_bf16_f32 v130, v148, v149
	v_cvt_pk_bf16_f32 v131, v150, v151
	v_cvt_pk_bf16_f32 v132, v152, v153
	v_cvt_pk_bf16_f32 v133, v154, v155
	v_cvt_pk_bf16_f32 v134, v156, v157
	v_cvt_pk_bf16_f32 v135, v158, v159
	v_cvt_pk_bf16_f32 v136, v208, v209
	v_cvt_pk_bf16_f32 v137, v210, v211
	v_cvt_pk_bf16_f32 v138, v216, v217
	v_cvt_pk_bf16_f32 v139, v218, v219
	v_cvt_pk_bf16_f32 v140, v222, v223
	v_cvt_pk_bf16_f32 v141, v224, v225
	v_cvt_pk_bf16_f32 v142, v245, v246
	v_cvt_pk_bf16_f32 v143, v247, v143
	v_add_u32_e32 v239, s2, v235
	s_nop 0
	v_permlane32_swap_b32_e32 v243, v244
	ds_read_b64_tr_b16 v[144:145], v239 offset:0
	ds_read_b64_tr_b16 v[146:147], v239 offset:0x800
	ds_read_b64_tr_b16 v[148:149], v239 offset:0x1000
	ds_read_b64_tr_b16 v[150:151], v239 offset:0x1800
	ds_read_b64_tr_b16 v[152:153], v239 offset:0x2000
	ds_read_b64_tr_b16 v[154:155], v239 offset:0x2800
	ds_read_b64_tr_b16 v[156:157], v239 offset:0x3000
	ds_read_b64_tr_b16 v[158:159], v239 offset:0x3800
	s_waitcnt lgkmcnt(0)
; __device__ __forceinline__ void partialSM(f32x16& p0, f32x16& p1, float& m_reg, float& mn, float& alpha) {
;   float pmax = p0[0];
; #pragma unroll
;   for (int r = 1; r < 16; ++r) pmax = fmaxf(pmax, p0[r]);
; #pragma unroll
;   for (int r = 0; r < 16; ++r) pmax = fmaxf(pmax, p1[r]);
;   { auto rr = __builtin_amdgcn_permlane32_swap(__float_as_uint(pmax), __float_as_uint(pmax), false, false);
;     pmax = fmaxf(__uint_as_float(rr[0]), __uint_as_float(rr[1])); }
;   if (__builtin_expect(__all(pmax - m_reg <= AT_THR * 1.4426950408889634f), 1)) { mn = m_reg; alpha = 1.f; }
;   else { mn = fmaxf(m_reg, pmax); alpha = __builtin_amdgcn_exp2f(m_reg - mn); m_reg = mn; }
; template <int D0> __device__ __forceinline__ void pv_one(f32x16& od, int vb, bf16x8 pa0, bf16x8 pa1, bf16x8 pa2, bf16x8 pa3) {
;     ...
;   od = __builtin_amdgcn_mfma_f32_32x32x16_bf16(pa0, PK(l0, h0), od, 0, 0, 0);
;   od = __builtin_amdgcn_mfma_f32_32x32x16_bf16(pa1, PK(l1, h1), od, 0, 0, 0);
;   od = __builtin_amdgcn_mfma_f32_32x32x16_bf16(pa2, PK(l2, h2), od, 0, 0, 0);
;   od = __builtin_amdgcn_mfma_f32_32x32x16_bf16(pa3, PK(l3, h3), od, 0, 0, 0);
;     ...
; }
; __device__ __forceinline__ void pv_d0(f32x16* o, int vb, bf16x8 pa0, bf16x8 pa1, bf16x8 pa2, bf16x8 pa3) {
;   pv_one<0>(o[0], vb, pa0, pa1, pa2, pa3); pv_one<1>(o[1], vb, pa0, pa1, pa2, pa3); pv_one<2>(o[2], vb, pa0, pa1, pa2, pa3); pv_one<3>(o[3], vb, pa0, pa1, pa2, pa3);
; }
; __device__ __forceinline__ void qkt2(f32x16& p0, f32x16& p1, const char* Ks, const bf16x8* qr, int r32, int hi, int cbase) {
; #pragma unroll
;   for (int r = 0; r < 16; ++r) { p0[r] = 0.f; p1[r] = 0.f; }
; #pragma unroll
;   for (int d0 = 0; d0 < 4; ++d0) { const int cb = cbase + (d0 * 16 + hi * 8) * 2;
;     const bf16x8 b0 = *reinterpret_cast<const bf16x8*>(Ks + KSWZ(r32, cb));
;     const bf16x8 b1 = *reinterpret_cast<const bf16x8*>(Ks + KSWZ(32 + r32, cb));
;     p0 = __builtin_amdgcn_mfma_f32_32x32x16_bf16(b0, qr[d0], p0, 0, 0, 0);
;     p1 = __builtin_amdgcn_mfma_f32_32x32x16_bf16(b1, qr[d0], p1, 0, 0, 0); }
; }
	s_nop 0
	v_mfma_f32_32x32x16_bf16 v[112:127], v[128:131], v[144:147], v[112:127]
	ds_read_b64_tr_b16 v[144:145], v239 offset:0x200
	ds_read_b64_tr_b16 v[146:147], v239 offset:0xa00
	v_mfma_f32_32x32x16_bf16 v[112:127], v[132:135], v[148:151], v[112:127]
	ds_read_b64_tr_b16 v[148:149], v239 offset:0x1200
	ds_read_b64_tr_b16 v[150:151], v239 offset:0x1a00
	v_mfma_f32_32x32x16_bf16 v[112:127], v[136:139], v[152:155], v[112:127]
	ds_read_b64_tr_b16 v[152:153], v239 offset:0x2200
	ds_read_b64_tr_b16 v[154:155], v239 offset:0x2a00
	v_mfma_f32_32x32x16_bf16 v[112:127], v[140:143], v[156:159], v[112:127]
	ds_read_b64_tr_b16 v[156:157], v239 offset:0x3200
	ds_read_b64_tr_b16 v[158:159], v239 offset:0x3a00
	s_waitcnt lgkmcnt(0)
	v_mfma_f32_32x32x16_bf16 v[96:111], v[128:131], v[144:147], v[96:111]
	ds_read_b64_tr_b16 v[144:145], v239 offset:0x400
	ds_read_b64_tr_b16 v[146:147], v239 offset:0xc00
	v_mfma_f32_32x32x16_bf16 v[96:111], v[132:135], v[148:151], v[96:111]
	ds_read_b64_tr_b16 v[148:149], v239 offset:0x1400
	ds_read_b64_tr_b16 v[150:151], v239 offset:0x1c00
	v_mfma_f32_32x32x16_bf16 v[96:111], v[136:139], v[152:155], v[96:111]
	ds_read_b64_tr_b16 v[152:153], v239 offset:0x2400
	ds_read_b64_tr_b16 v[154:155], v239 offset:0x2c00
	v_mfma_f32_32x32x16_bf16 v[96:111], v[140:143], v[156:159], v[96:111]
	ds_read_b64_tr_b16 v[156:157], v239 offset:0x3400
	ds_read_b64_tr_b16 v[158:159], v239 offset:0x3c00
	s_waitcnt lgkmcnt(0)
	v_mfma_f32_32x32x16_bf16 v[80:95], v[128:131], v[144:147], v[80:95]
	ds_read_b64_tr_b16 v[144:145], v239 offset:0x600
	ds_read_b64_tr_b16 v[146:147], v239 offset:0xe00
	v_mfma_f32_32x32x16_bf16 v[80:95], v[132:135], v[148:151], v[80:95]
	ds_read_b64_tr_b16 v[148:149], v239 offset:0x1600
	ds_read_b64_tr_b16 v[150:151], v239 offset:0x1e00
	v_mfma_f32_32x32x16_bf16 v[80:95], v[136:139], v[152:155], v[80:95]
	ds_read_b64_tr_b16 v[152:153], v239 offset:0x2600
	ds_read_b64_tr_b16 v[154:155], v239 offset:0x2e00
	v_mfma_f32_32x32x16_bf16 v[80:95], v[140:143], v[156:159], v[80:95]
	ds_read_b64_tr_b16 v[156:157], v239 offset:0x3600
	ds_read_b64_tr_b16 v[158:159], v239 offset:0x3e00
	s_waitcnt lgkmcnt(0)
	v_mfma_f32_32x32x16_bf16 v[48:63], v[128:131], v[144:147], v[48:63]
	v_add3_u32 v128, s2, v231, v206
	ds_read_b128 v[128:131], v128
	v_add3_u32 v208, s2, v232, v206
	ds_read_b128 v[208:211], v208
	v_add_u32_e32 v216, v242, v232
	ds_read_b128 v[222:225], v216 offset:8192
	v_add_u32_e32 v216, v242, v233
	v_mfma_f32_32x32x16_bf16 v[48:63], v[132:135], v[148:151], v[48:63]
	v_add_u32_e32 v132, v242, v231
	ds_read_b128 v[132:135], v132 offset:8192
	v_mfma_f32_32x32x16_bf16 v[48:63], v[136:139], v[152:155], v[48:63]
	v_mfma_f32_32x32x16_bf16 v[48:63], v[140:143], v[156:159], v[48:63]
	s_waitcnt lgkmcnt(0)
	v_mfma_f32_32x32x16_bf16 v[144:159], v[128:131], v[176:179], 0
	v_mfma_f32_32x32x16_bf16 v[144:159], v[208:211], v[180:183], v[144:159]
	v_add3_u32 v208, s2, v233, v206
	ds_read_b128 v[208:211], v208
	v_mfma_f32_32x32x16_bf16 v[128:143], v[132:135], v[176:179], 0
	v_mfma_f32_32x32x16_bf16 v[128:143], v[222:225], v[180:183], v[128:143]
	ds_read_b128 v[222:225], v216 offset:8192
	v_add_u32_e32 v216, v242, v234
	s_waitcnt lgkmcnt(0)
	v_mfma_f32_32x32x16_bf16 v[144:159], v[208:211], v[184:187], v[144:159]
	v_add3_u32 v208, s2, v234, v206
	ds_read_b128 v[208:211], v208
	v_mfma_f32_32x32x16_bf16 v[128:143], v[222:225], v[184:187], v[128:143]
	ds_read_b128 v[222:225], v216 offset:8192
	s_waitcnt lgkmcnt(0)
	v_mfma_f32_32x32x16_bf16 v[144:159], v[208:211], v[188:191], v[144:159]
	v_mfma_f32_32x32x16_bf16 v[128:143], v[222:225], v[188:191], v[128:143]
	s_nop 10
	v_max3_f32 v208, v144, v145, v146
	v_max3_f32 v209, v152, v153, v154
	v_max3_f32 v208, v208, v147, v148
	v_max3_f32 v209, v209, v155, v156
	v_max3_f32 v208, v208, v149, v150
	v_max3_f32 v209, v209, v157, v158
	v_max3_f32 v208, v208, v151, v159
	v_max3_f32 v210, v128, v129, v130
	v_max3_f32 v211, v136, v137, v138
	v_max3_f32 v210, v210, v131, v132
	v_max3_f32 v211, v211, v139, v140
	v_max3_f32 v210, v210, v133, v134
	v_max3_f32 v211, v211, v141, v142
	v_max3_f32 v210, v210, v135, v143
	v_max3_f32 v208, v208, v209, v210
	v_max_f32_e32 v208, v208, v211
	v_mov_b32_e32 v209, v208
	s_nop 1
	v_permlane32_swap_b32_e32 v208, v209
	v_max_f32_e32 v242, v208, v209
	v_sub_f32_e32 v208, v242, v241
	v_cmp_ge_f32_e32 vcc, s0, v208
	s_cmp_lg_u64 vcc, exec
	s_cbranch_scc1 .LBB0_142
	v_mov_b32_e32 v246, v241
	v_mov_b32_e32 v245, 1.0
	v_mov_b32_e32 v242, v241
	s_branch .LBB0_139

; __device__ __forceinline__ void finishSM(f32x16& p0, f32x16& p1, float alpha, float& l_reg, bf16x8& pa0, bf16x8& pa1, bf16x8& pa2, bf16x8& pa3) {
; #pragma unroll
;   for (int r = 0; r < 16; ++r) p1[r] = __builtin_amdgcn_exp2f(p1[r]);
;   float ps = 0;
; #pragma unroll
;   for (int r = 0; r < 16; ++r) ps += p0[r];
; #pragma unroll
;   for (int r = 0; r < 16; ++r) ps += p1[r];
;   { auto rr = __builtin_amdgcn_permlane32_swap(__float_as_uint(ps), __float_as_uint(ps), false, false);
;     ps = __uint_as_float(rr[0]) + __uint_as_float(rr[1]); }
;   l_reg = l_reg * alpha + ps;
;     ...
;   PK4(p0, 0, pa0); PK4(p0, 8, pa1); PK4(p1, 0, pa2); PK4(p1, 8, pa3);
;     ...
; }
; template <int D0> __device__ __forceinline__ void pv_one(f32x16& od, int vb, bf16x8 pa0, bf16x8 pa1, bf16x8 pa2, bf16x8 pa3) {
;     ...
;   od = __builtin_amdgcn_mfma_f32_32x32x16_bf16(pa0, PK(l0, h0), od, 0, 0, 0);
;   od = __builtin_amdgcn_mfma_f32_32x32x16_bf16(pa1, PK(l1, h1), od, 0, 0, 0);
;   od = __builtin_amdgcn_mfma_f32_32x32x16_bf16(pa2, PK(l2, h2), od, 0, 0, 0);
;   od = __builtin_amdgcn_mfma_f32_32x32x16_bf16(pa3, PK(l3, h3), od, 0, 0, 0);
;     ...
; }
; __device__ __forceinline__ void pv_d0(f32x16* o, int vb, bf16x8 pa0, bf16x8 pa1, bf16x8 pa2, bf16x8 pa3) {
;   pv_one<0>(o[0], vb, pa0, pa1, pa2, pa3); pv_one<1>(o[1], vb, pa0, pa1, pa2, pa3); pv_one<2>(o[2], vb, pa0, pa1, pa2, pa3); pv_one<3>(o[3], vb, pa0, pa1, pa2, pa3);
.LBB0_139:
	v_sub_f32_e32 v144, v144, v246
	v_sub_f32_e32 v145, v145, v246
	v_exp_f32_e32 v144, v144
	v_sub_f32_e32 v146, v146, v246
	v_exp_f32_e32 v145, v145
	v_sub_f32_e32 v147, v147, v246
	v_exp_f32_e32 v146, v146
	v_sub_f32_e32 v148, v148, v246
	v_sub_f32_e32 v128, v128, v246
	v_exp_f32_e32 v147, v147
	v_sub_f32_e32 v149, v149, v246
	v_exp_f32_e32 v148, v148
	v_exp_f32_e32 v209, v128
	v_sub_f32_e32 v150, v150, v246
	v_exp_f32_e32 v149, v149
	v_add_f32_e32 v128, v145, v144
	v_sub_f32_e32 v151, v151, v246
	v_exp_f32_e32 v150, v150
	v_add_f32_e32 v128, v146, v128
	v_sub_f32_e32 v152, v152, v246
	v_exp_f32_e32 v151, v151
	v_add_f32_e32 v128, v147, v128
	v_sub_f32_e32 v153, v153, v246
	v_exp_f32_e32 v152, v152
	v_add_f32_e32 v128, v148, v128
	v_sub_f32_e32 v154, v154, v246
	v_exp_f32_e32 v153, v153
	v_add_f32_e32 v128, v149, v128
	v_sub_f32_e32 v155, v155, v246
	v_exp_f32_e32 v154, v154
	v_add_f32_e32 v128, v150, v128
	v_sub_f32_e32 v156, v156, v246
	v_exp_f32_e32 v155, v155
	v_add_f32_e32 v128, v151, v128
	v_sub_f32_e32 v157, v157, v246
	v_exp_f32_e32 v156, v156
	v_add_f32_e32 v128, v152, v128
	v_sub_f32_e32 v158, v158, v246
	v_exp_f32_e32 v157, v157
	v_add_f32_e32 v128, v153, v128
	v_sub_f32_e32 v159, v159, v246
	v_exp_f32_e32 v158, v158
	v_add_f32_e32 v128, v154, v128
	v_exp_f32_e32 v159, v159
	v_add_f32_e32 v128, v155, v128
	v_sub_f32_e32 v129, v129, v246
	v_add_f32_e32 v128, v156, v128
	v_sub_f32_e32 v130, v130, v246
	v_exp_f32_e32 v210, v129
	v_add_f32_e32 v128, v157, v128
	v_sub_f32_e32 v131, v131, v246
	v_exp_f32_e32 v211, v130
	v_add_f32_e32 v128, v158, v128
	v_sub_f32_e32 v208, v132, v246
	v_exp_f32_e32 v216, v131
	v_add_f32_e32 v128, v159, v128
	v_sub_f32_e32 v133, v133, v246
	v_exp_f32_e32 v208, v208
	v_add_f32_e32 v128, v209, v128
	v_sub_f32_e32 v134, v134, v246
	v_exp_f32_e32 v217, v133
	v_add_f32_e32 v128, v210, v128
	v_sub_f32_e32 v135, v135, v246
	v_exp_f32_e32 v218, v134
	v_add_f32_e32 v128, v211, v128
	v_sub_f32_e32 v136, v136, v246
	v_exp_f32_e32 v219, v135
	v_add_f32_e32 v128, v216, v128
	v_sub_f32_e32 v137, v137, v246
	v_exp_f32_e32 v222, v136
	v_add_f32_e32 v128, v208, v128
	v_sub_f32_e32 v138, v138, v246
	v_exp_f32_e32 v223, v137
	v_add_f32_e32 v128, v217, v128
	v_sub_f32_e32 v139, v139, v246
	v_exp_f32_e32 v224, v138
	v_add_f32_e32 v128, v218, v128
	v_sub_f32_e32 v140, v140, v246
	v_add_f32_e32 v132, v243, v244
	v_exp_f32_e32 v225, v139
	v_add_f32_e32 v128, v219, v128
	v_sub_f32_e32 v141, v141, v246
	v_fmac_f32_e32 v132, v238, v240
	v_exp_f32_e32 v238, v140
	v_add_f32_e32 v128, v222, v128
	v_sub_f32_e32 v142, v142, v246
	v_exp_f32_e32 v240, v141
	v_add_f32_e32 v128, v223, v128
	v_sub_f32_e32 v143, v143, v246
	v_exp_f32_e32 v241, v142
	v_add_f32_e32 v128, v224, v128
	v_exp_f32_e32 v243, v143
	v_add_f32_e32 v128, v225, v128
	v_add_f32_e32 v128, v238, v128
	v_add_f32_e32 v128, v240, v128
	v_add_f32_e32 v128, v241, v128
	v_add_f32_e32 v128, v243, v128
	v_mov_b32_e32 v129, v128
	s_nop 1
	v_permlane32_swap_b32_e32 v128, v129
	v_add_f32_e32 v133, v128, v129
	v_fmac_f32_e32 v133, v237, v245
	v_cvt_pk_bf16_f32 v128, v144, v145
	v_cvt_pk_bf16_f32 v129, v146, v147
	v_cvt_pk_bf16_f32 v130, v148, v149
	v_cvt_pk_bf16_f32 v131, v150, v151
	v_cvt_pk_bf16_f32 v134, v152, v153
	v_cvt_pk_bf16_f32 v135, v154, v155
	v_cvt_pk_bf16_f32 v136, v156, v157
	v_cvt_pk_bf16_f32 v137, v158, v159
	v_cvt_pk_bf16_f32 v138, v209, v210
	v_cvt_pk_bf16_f32 v139, v211, v216
	v_cvt_pk_bf16_f32 v140, v208, v217
	v_cvt_pk_bf16_f32 v141, v218, v219
	v_cvt_pk_bf16_f32 v142, v222, v223
	v_cvt_pk_bf16_f32 v143, v224, v225
	v_cvt_pk_bf16_f32 v144, v238, v240
	v_cvt_pk_bf16_f32 v145, v241, v243
	ds_read_b64_tr_b16 v[146:147], v239 offset:0
	ds_read_b64_tr_b16 v[148:149], v239 offset:0x800
	ds_read_b64_tr_b16 v[150:151], v239 offset:0x1000
	ds_read_b64_tr_b16 v[152:153], v239 offset:0x1800
	ds_read_b64_tr_b16 v[154:155], v239 offset:0x2000
	ds_read_b64_tr_b16 v[156:157], v239 offset:0x2800
	ds_read_b64_tr_b16 v[208:209], v239 offset:0x3000
	ds_read_b64_tr_b16 v[210:211], v239 offset:0x3800
	s_waitcnt lgkmcnt(0)
	s_nop 0
	v_mfma_f32_32x32x16_bf16 v[0:15], v[128:131], v[146:149], v[0:15]
	ds_read_b64_tr_b16 v[146:147], v239 offset:0x200
	ds_read_b64_tr_b16 v[148:149], v239 offset:0xa00
	v_mfma_f32_32x32x16_bf16 v[0:15], v[134:137], v[150:153], v[0:15]
	ds_read_b64_tr_b16 v[150:151], v239 offset:0x1200
	ds_read_b64_tr_b16 v[152:153], v239 offset:0x1a00
	v_mfma_f32_32x32x16_bf16 v[0:15], v[138:141], v[154:157], v[0:15]
	ds_read_b64_tr_b16 v[154:155], v239 offset:0x2200
	ds_read_b64_tr_b16 v[156:157], v239 offset:0x2a00
	v_mfma_f32_32x32x16_bf16 v[0:15], v[142:145], v[208:211], v[0:15]
	ds_read_b64_tr_b16 v[208:209], v239 offset:0x3200
	ds_read_b64_tr_b16 v[210:211], v239 offset:0x3a00
	s_waitcnt lgkmcnt(0)
	v_mfma_f32_32x32x16_bf16 v[64:79], v[128:131], v[146:149], v[64:79]
	ds_read_b64_tr_b16 v[146:147], v239 offset:0x400
	ds_read_b64_tr_b16 v[148:149], v239 offset:0xc00
	v_mfma_f32_32x32x16_bf16 v[64:79], v[134:137], v[150:153], v[64:79]
	ds_read_b64_tr_b16 v[150:151], v239 offset:0x1400
	ds_read_b64_tr_b16 v[152:153], v239 offset:0x1c00
	v_mfma_f32_32x32x16_bf16 v[64:79], v[138:141], v[154:157], v[64:79]
	ds_read_b64_tr_b16 v[154:155], v239 offset:0x2400
	ds_read_b64_tr_b16 v[156:157], v239 offset:0x2c00
	v_mfma_f32_32x32x16_bf16 v[64:79], v[142:145], v[208:211], v[64:79]
	ds_read_b64_tr_b16 v[208:209], v239 offset:0x3400
	ds_read_b64_tr_b16 v[210:211], v239 offset:0x3c00
	s_waitcnt lgkmcnt(0)
	v_mfma_f32_32x32x16_bf16 v[32:47], v[128:131], v[146:149], v[32:47]
	ds_read_b64_tr_b16 v[146:147], v239 offset:0x600
	ds_read_b64_tr_b16 v[148:149], v239 offset:0xe00
	v_mfma_f32_32x32x16_bf16 v[32:47], v[134:137], v[150:153], v[32:47]
	ds_read_b64_tr_b16 v[150:151], v239 offset:0x1600
	ds_read_b64_tr_b16 v[152:153], v239 offset:0x1e00
	v_mfma_f32_32x32x16_bf16 v[32:47], v[138:141], v[154:157], v[32:47]
	ds_read_b64_tr_b16 v[154:155], v239 offset:0x2600
	ds_read_b64_tr_b16 v[156:157], v239 offset:0x2e00
	v_mfma_f32_32x32x16_bf16 v[32:47], v[142:145], v[208:211], v[32:47]
	ds_read_b64_tr_b16 v[208:209], v239 offset:0x3600
	ds_read_b64_tr_b16 v[210:211], v239 offset:0x3e00
	s_waitcnt lgkmcnt(0)
	v_mfma_f32_32x32x16_bf16 v[16:31], v[128:131], v[146:149], v[16:31]
	s_waitcnt vmcnt(0)
	s_add_u32 s48, s48, 0xa0000
	s_addc_u32 s49, s49, 0
	s_add_i32 s60, s60, 1
	s_mul_i32 s2, s33, 0xa0000
	s_cmp_eq_u32 s2, s48
	s_waitcnt vmcnt(0)
	v_mfma_f32_32x32x16_bf16 v[16:31], v[134:137], v[150:153], v[16:31]
	s_barrier
	v_mfma_f32_32x32x16_bf16 v[16:31], v[138:141], v[154:157], v[16:31]
	v_mfma_f32_32x32x16_bf16 v[16:31], v[142:145], v[208:211], v[16:31]
	s_cbranch_scc1 .LBB0_143
	v_mov_b32_e32 v237, v133
	v_mov_b32_e32 v238, v132
	v_mov_b32_e32 v241, v242
	v_mov_b32_e32 v243, v236
	s_branch .LBB0_121
